# v27 + diff attention loop-edge edits: latch scalar work ahead of the step barrier, no-rescale branch straight to the PV block, m0 written directly in the LDS-DMA head
# baseline (speedup 1.0000x reference)
; template <int DQK>
; __device__ __forceinline__ void attn_pass4(LAS unsigned char* lds, const bf16* Qp, int qpitch, const bf16* Kp, int kpitch, const bf16* Vp, int vpitch, int q0, f32x16 (&o)[4], float (&rl)[16]) {
;     ...
;         for (int t = 0; t < NT; ++t) {
;             const int vnext = ATT_VNEXT(vcur);
;             if (t + 1 < NT) ATT_DMA(t + 1, (t + 1) & 1, vnext);
.LBB0_621:
	s_add_i32 s25, s24, 1
	s_cmp_lg_u32 s24, 2
	s_cselect_b32 s35, s25, 0
	s_add_i32 s25, s72, 1
	s_cmp_ge_u32 s25, s31
	s_cbranch_scc1 .LBB0_625
	s_bitcmp1_b32 s25, 0
	s_cselect_b32 s73, 0x2400, 0
	s_add_i32 m0, s73, s5
	s_andn2_b64 vcc, exec, s[10:11]
	global_load_lds_dwordx4 v170, s[70:71]
	s_cbranch_vccnz .LBB0_624
	s_add_i32 m0, s73, s80
	s_nop 0
	global_load_lds_dwordx4 v176, s[70:71]
.LBB0_624:
	s_mul_i32 s73, s35, 0x5000
	s_add_i32 s73, s26, s73
	s_mov_b32 m0, s73
	s_add_u32 s74, s70, 0x4000000
	s_addc_u32 s75, s71, 0
	global_load_lds_dwordx4 v172, s[74:75]
	s_add_i32 m0, s73, 0x2000
	v_readfirstlane_b32 s32, v242
	global_load_lds_dwordx4 v174, s[74:75]
	s_cmpk_gt_u32 s32, 0xff
	s_cbranch_scc1 .Lskip_v2_0
	s_add_i32 m0, s73, 0x4000
	v_lshl_add_u64 v[114:115], s[74:75], 0, v[178:179]
	global_load_lds_dwordx4 v[114:115], off

; #define ATT_BAR() asm volatile("s_waitcnt lgkmcnt(0)\n\ts_barrier" ::: "memory")
; #define ATT_BAR() asm volatile("s_waitcnt vmcnt(0) lgkmcnt(0)\n\ts_barrier" ::: "memory")
; template <int DQK>
; __device__ __forceinline__ void attn_pass4(LAS unsigned char* lds, const bf16* Qp, int qpitch, const bf16* Kp, int kpitch, const bf16* Vp, int vpitch, int q0, f32x16 (&o)[4], float (&rl)[16]) {
;     ...
;         for (int t = 0; t < NT; ++t) {
;             const int vnext = ATT_VNEXT(vcur);
;             if (t + 1 < NT) ATT_DMA(t + 1, (t + 1) & 1, vnext);
;             if (ATT_VIS(t)) { ATT_A(t); ATT_B(vcur); }
;             vcur = vnext;
;             ATT_BAR();
.LBB0_638:
	s_add_i32 s18, s18, 64
	s_add_u32 s70, s70, 0x20000
	s_addc_u32 s71, s71, 0
	s_mov_b32 s24, s35
	s_mov_b32 s72, s25
	s_cmp_eq_u32 s31, s25
	s_waitcnt vmcnt(0) lgkmcnt(0)
	s_barrier
	s_cbranch_scc1 .LBB0_641
	s_branch .LBB0_621

; template <int DQK>
; __device__ __forceinline__ void attn_pass4(LAS unsigned char* lds, const bf16* Qp, int qpitch, const bf16* Kp, int kpitch, const bf16* Vp, int vpitch, int q0, f32x16 (&o)[4], float (&rl)[16]) {
;     ...
;         for (int t = 0; t < NT; ++t) {
;             const int vnext = ATT_VNEXT(vcur);
;             if (t + 1 < NT) ATT_DMA(t + 1, (t + 1) & 1, vnext);
.LBB0_821:
	s_add_i32 s24, s35, 1
	s_cmp_lg_u32 s35, 2
	s_cselect_b32 s24, s24, 0
	s_add_i32 s25, s72, 1
	s_cmp_ge_u32 s25, s31
	s_cbranch_scc1 .LBB0_825
	s_bitcmp1_b32 s25, 0
	s_cselect_b32 s73, 0x2400, 0
	s_add_i32 m0, s73, s3
	s_andn2_b64 vcc, exec, s[10:11]
	global_load_lds_dwordx4 v170, s[70:71]
	s_cbranch_vccnz .LBB0_824
	s_add_i32 m0, s73, s27
	s_nop 0
	global_load_lds_dwordx4 v176, s[70:71]
.LBB0_824:
	s_mul_i32 s73, s24, 0x5000
	s_add_i32 s73, s5, s73
	s_mov_b32 m0, s73
	s_add_u32 s74, s70, 0x3ffff80
	s_addc_u32 s75, s71, 0
	global_load_lds_dwordx4 v172, s[74:75]
	s_add_i32 m0, s73, 0x2000
	v_readfirstlane_b32 s32, v242
	global_load_lds_dwordx4 v174, s[74:75]
	s_cmpk_gt_u32 s32, 0xff
	s_cbranch_scc1 .Lskip_v2_1
	s_add_i32 m0, s73, 0x4000
	v_lshl_add_u64 v[114:115], s[74:75], 0, v[178:179]
	global_load_lds_dwordx4 v[114:115], off

; #define ATT_BAR() asm volatile("s_waitcnt lgkmcnt(0)\n\ts_barrier" ::: "memory")
; #define ATT_BAR() asm volatile("s_waitcnt vmcnt(0) lgkmcnt(0)\n\ts_barrier" ::: "memory")
; template <int DQK>
; __device__ __forceinline__ void attn_pass4(LAS unsigned char* lds, const bf16* Qp, int qpitch, const bf16* Kp, int kpitch, const bf16* Vp, int vpitch, int q0, f32x16 (&o)[4], float (&rl)[16]) {
;     ...
;         for (int t = 0; t < NT; ++t) {
;             const int vnext = ATT_VNEXT(vcur);
;             if (t + 1 < NT) ATT_DMA(t + 1, (t + 1) & 1, vnext);
;             if (ATT_VIS(t)) { ATT_A(t); ATT_B(vcur); }
;             vcur = vnext;
;             ATT_BAR();
.LBB0_838:
	s_add_i32 s18, s18, 64
	s_add_u32 s70, s70, 0x20000
	s_addc_u32 s71, s71, 0
	s_mov_b32 s72, s25
	s_cmp_eq_u32 s31, s25
	s_waitcnt vmcnt(0) lgkmcnt(0)
	s_barrier
	s_cbranch_scc1 .LBB0_841
	s_mov_b32 s35, s24
	s_branch .LBB0_821
